# workgroups that finish FFN-out/Wo early (no context-row split-K item) read the first half of the residual stream while they wait, so the following norm phase finds it in cache
# baseline (speedup 1.0000x reference)
; #define PG8_WAIT_V(n) asm volatile("s_waitcnt vmcnt(" #n ")" ::: "memory")
; #define PG8_BAR __builtin_amdgcn_s_barrier()
; template <class Epi, class Sched, bool ALIGN_EPI = false, bool SP2 = false>
; __device__ __forceinline__ void gemm_phase(PG8_LAS unsigned char* lds, const Gemm g, const Sched& S, const Epi& E, const int tid_in) {
;     ...
;     PG8_WAIT_V(0);
;     if constexpr (!ALIGN_EPI) { if (wr == 0) PG8_BAR; }
;     PG8_BAR;
.LBB0_297:
	s_cmpk_lt_u32 s72, 0x400
	s_cbranch_scc1 pfh_skip
	s_sub_i32 s4, s72, 0x400
	s_add_i32 s4, s4, s62
	s_lshl_b32 s4, s4, 10
	v_mbcnt_lo_u32_b32 v204, -1, 0
	v_mbcnt_hi_u32_b32 v204, -1, v204
	v_lshlrev_b32_e32 v204, 4, v204
	v_add_u32_e32 v204, s4, v204
	s_mov_b64 s[2:3], s[98:99]
	s_mov_b32 s4, 0
pfh_loop:
	global_load_dwordx4 v[200:203], v204, s[2:3]
	s_add_u32 s2, s2, 0x100000
	s_addc_u32 s3, s3, 0
	s_add_i32 s4, s4, 1
	s_cmp_lt_u32 s4, 32
	s_cbranch_scc1 pfh_loop
pfh_skip:
	s_waitcnt vmcnt(0)
	v_readlane_b32 s58, v255, 5
	s_barrier
	s_movk_i32 s47, 0xffd0
	s_mov_b32 s38, s62
	v_readlane_b32 s59, v255, 6
	v_readlane_b32 s91, v255, 7
